# P5: forget-gate scans spread one per workgroup, compress-input embedding loads batched per row; P7: row value prefetched one trip ahead (on bundle6)
# speedup vs baseline: 1.0110x; 1.0054x over previous
.LBB0_575:
	v_bfe_u32 v0, v32, 1, 8
	v_cmp_ne_u32_e64 s[4:5], s30, v0
	s_and_saveexec_b64 s[10:11], s[4:5]
	s_xor_b64 s[10:11], exec, s[10:11]
	s_cbranch_execz .LBB0_579
	v_and_or_b32 v1, v29, s31, v27
	v_lshl_add_u32 v23, v0, 4, v1
	v_mov_b64_e32 v[0:1], s[14:15]
	v_mad_u64_u32 v[0:1], s[4:5], v23, s33, v[0:1]
	v_cmp_gt_u32_e64 s[4:5], s34, v32
	v_and_b32_e32 v2, 64, v28
	v_mov_b32_e32 v25, v17
	v_cndmask_b32_e64 v16, v30, v31, s[4:5]
	v_lshl_add_u64 v[0:1], v[0:1], 0, v[16:17]
	v_lshlrev_b32_e32 v16, 1, v2
	v_lshl_add_u64 v[0:1], v[0:1], 0, v[16:17]
	v_lshl_add_u64 v[12:13], v[0:1], 0, v[24:25]
	global_load_dwordx4 v[0:3], v[12:13], off offset:48
	global_load_dwordx4 v[4:7], v[12:13], off offset:32
	global_load_dwordx4 v[8:11], v[12:13], off offset:16
	s_nop 0
	global_load_dwordx4 v[12:15], v[12:13], off
	v_mov_b32_e32 v76, s21
	v_mov_b32_e32 v77, s19
	v_cndmask_b32_e64 v79, v76, v77, s[4:5]
	v_mov_b32_e32 v76, s20
	v_mov_b32_e32 v77, s18
	v_cndmask_b32_e64 v78, v76, v77, s[4:5]
	v_mov_b32_e32 v76, v22
	v_mov_b32_e32 v77, v17
	v_lshl_add_u64 v[78:79], v[78:79], 0, v[76:77]
	v_lshlrev_b32_e32 v76, 2, v18
	v_lshl_add_u64 v[78:79], v[78:79], 0, v[76:77]
	global_load_dwordx4 v[80:83], v[78:79], off
	global_load_dwordx4 v[84:87], v[78:79], off offset:16
	global_load_dwordx4 v[88:91], v[78:79], off offset:32
	global_load_dwordx4 v[92:95], v[78:79], off offset:48
	global_load_dwordx4 v[96:99], v[78:79], off offset:64
	global_load_dwordx4 v[100:103], v[78:79], off offset:80
	global_load_dwordx4 v[104:107], v[78:79], off offset:96
	global_load_dwordx4 v[108:111], v[78:79], off offset:112
	s_and_b64 s[36:37], vcc, s[4:5]
	s_and_saveexec_b64 s[28:29], s[36:37]
	s_cbranch_execz .LBB0_578
	v_lshlrev_b32_e32 v16, 2, v23
	global_load_dword v16, v16, s[16:17]
	s_waitcnt vmcnt(1)
	v_lshlrev_b32_e32 v34, 16, v12
	v_and_b32_e32 v35, 0xffff0000, v12
	v_lshlrev_b32_e32 v36, 16, v8
	v_and_b32_e32 v37, 0xffff0000, v8
	v_lshlrev_b32_e32 v12, 16, v13
	v_and_b32_e32 v13, 0xffff0000, v13
	v_lshlrev_b32_e32 v8, 16, v9
	v_and_b32_e32 v9, 0xffff0000, v9
	v_lshlrev_b32_e32 v38, 16, v14
	v_and_b32_e32 v39, 0xffff0000, v14
	v_lshlrev_b32_e32 v40, 16, v10
	v_and_b32_e32 v41, 0xffff0000, v10
	v_lshlrev_b32_e32 v14, 16, v15
	v_and_b32_e32 v15, 0xffff0000, v15
	v_lshlrev_b32_e32 v10, 16, v11
	v_and_b32_e32 v11, 0xffff0000, v11
	s_waitcnt vmcnt(0)
	v_cvt_f32_i32_e32 v16, v16
	v_cvt_f64_f32_e32 v[42:43], v16
	v_mul_f32_e32 v23, 0x3e4693b0, v16
	v_mul_f32_e32 v25, 0x3d1a08c8, v16
	v_mul_f32_e32 v33, 0x3beef74e, v16
	v_mul_f32_e32 v52, 0x3ab95d22, v16
	v_mul_f32_e32 v54, 0x398fc8f7, v16
	v_mul_f32_e32 v56, 0x385f10c4, v16
	v_mul_f32_e32 v16, 0x372d07a7, v16
	v_mul_f64 v[44:45], v[42:43], s[26:27]
	v_cvt_f64_f32_e32 v[46:47], v23
	v_cvt_f64_f32_e32 v[48:49], v25
	v_cvt_f64_f32_e32 v[50:51], v33
	v_cvt_f64_f32_e32 v[52:53], v52
	v_cvt_f64_f32_e32 v[54:55], v54
	v_cvt_f64_f32_e32 v[56:57], v56
	v_cvt_f64_f32_e32 v[58:59], v16
	v_rndne_f64_e32 v[44:45], v[44:45]
	v_mul_f64 v[60:61], v[46:47], s[26:27]
	v_mul_f64 v[62:63], v[48:49], s[26:27]
	v_mul_f64 v[66:67], v[50:51], s[26:27]
	v_mul_f64 v[68:69], v[52:53], s[26:27]
	v_mul_f64 v[70:71], v[54:55], s[26:27]
	v_mul_f64 v[72:73], v[56:57], s[26:27]
	v_mul_f64 v[74:75], v[58:59], s[26:27]
	v_fma_f64 v[42:43], v[42:43], s[26:27], -v[44:45]
	v_rndne_f64_e32 v[44:45], v[60:61]
	v_rndne_f64_e32 v[60:61], v[62:63]
	v_rndne_f64_e32 v[62:63], v[66:67]
	v_rndne_f64_e32 v[66:67], v[68:69]
	v_rndne_f64_e32 v[68:69], v[70:71]
	v_rndne_f64_e32 v[70:71], v[72:73]
	v_rndne_f64_e32 v[72:73], v[74:75]
	v_cvt_f32_f64_e32 v16, v[42:43]
	v_fma_f64 v[42:43], v[46:47], s[26:27], -v[44:45]
	v_fma_f64 v[44:45], v[48:49], s[26:27], -v[60:61]
	v_fma_f64 v[46:47], v[50:51], s[26:27], -v[62:63]
	v_fma_f64 v[48:49], v[52:53], s[26:27], -v[66:67]
	v_fma_f64 v[50:51], v[54:55], s[26:27], -v[68:69]
	v_fma_f64 v[52:53], v[56:57], s[26:27], -v[70:71]
	v_fma_f64 v[54:55], v[58:59], s[26:27], -v[72:73]
	v_sin_f32_e32 v56, v16
	v_cos_f32_e32 v58, v16
	v_cvt_f32_f64_e32 v16, v[42:43]
	v_cvt_f32_f64_e32 v23, v[44:45]
	v_cvt_f32_f64_e32 v25, v[46:47]
	v_cvt_f32_f64_e32 v33, v[48:49]
	v_cvt_f32_f64_e32 v49, v[50:51]
	v_cvt_f32_f64_e32 v51, v[52:53]
	v_cvt_f32_f64_e32 v53, v[54:55]
	v_sin_f32_e32 v57, v16
	v_sin_f32_e32 v42, v23
	v_sin_f32_e32 v43, v25
	v_sin_f32_e32 v46, v33
	v_sin_f32_e32 v47, v49
	v_sin_f32_e32 v50, v51
	v_cos_f32_e32 v52, v51
	v_sin_f32_e32 v51, v53
	v_cos_f32_e32 v59, v16
	v_cos_f32_e32 v44, v23
	v_cos_f32_e32 v45, v25
	v_cos_f32_e32 v48, v33
	v_cos_f32_e32 v49, v49
	v_cos_f32_e32 v53, v53
	v_pk_mul_f32 v[54:55], v[56:57], v[34:35]
	v_pk_mul_f32 v[56:57], v[56:57], v[36:37]
	v_pk_mul_f32 v[60:61], v[42:43], v[12:13]
	v_pk_mul_f32 v[42:43], v[42:43], v[8:9]
	v_pk_mul_f32 v[62:63], v[46:47], v[38:39]
	v_pk_mul_f32 v[46:47], v[46:47], v[40:41]
	v_pk_mul_f32 v[66:67], v[50:51], v[14:15]
	v_pk_mul_f32 v[50:51], v[50:51], v[10:11]
	v_pk_fma_f32 v[36:37], v[58:59], v[36:37], v[54:55]
	v_pk_fma_f32 v[34:35], v[58:59], v[34:35], v[56:57] neg_lo:[0,0,1] neg_hi:[0,0,1]
	v_pk_fma_f32 v[54:55], v[44:45], v[8:9], v[60:61]
	v_pk_fma_f32 v[8:9], v[44:45], v[12:13], v[42:43] neg_lo:[0,0,1] neg_hi:[0,0,1]
	v_pk_fma_f32 v[40:41], v[48:49], v[40:41], v[62:63]
	v_pk_fma_f32 v[38:39], v[48:49], v[38:39], v[46:47] neg_lo:[0,0,1] neg_hi:[0,0,1]
	v_pk_fma_f32 v[42:43], v[52:53], v[10:11], v[66:67]
	v_pk_fma_f32 v[10:11], v[52:53], v[14:15], v[50:51] neg_lo:[0,0,1] neg_hi:[0,0,1]
	v_cvt_pk_bf16_f32 v12, v34, v35
	v_cvt_pk_bf16_f32 v13, v8, v9
	v_cvt_pk_bf16_f32 v14, v38, v39
	v_cvt_pk_bf16_f32 v15, v10, v11
	v_cvt_pk_bf16_f32 v8, v36, v37
	v_cvt_pk_bf16_f32 v9, v54, v55
	v_cvt_pk_bf16_f32 v10, v40, v41
	v_cvt_pk_bf16_f32 v11, v42, v43
.LBB0_578:
	s_or_b64 exec, exec, s[28:29]
	s_waitcnt vmcnt(0)
	v_lshlrev_b32_e32 v44, 16, v12
	v_and_b32_e32 v45, 0xffff0000, v12
	v_lshlrev_b32_e32 v12, 16, v13
	v_and_b32_e32 v13, 0xffff0000, v13
	v_lshlrev_b32_e32 v46, 16, v14
	v_and_b32_e32 v47, 0xffff0000, v14
	v_lshlrev_b32_e32 v14, 16, v15
	v_and_b32_e32 v15, 0xffff0000, v15
	v_pk_add_f32 v[80:81], v[80:81], v[44:45]
	v_pk_add_f32 v[82:83], v[82:83], v[12:13]
	v_pk_add_f32 v[84:85], v[84:85], v[46:47]
	v_pk_add_f32 v[86:87], v[86:87], v[14:15]
	v_cvt_pk_bf16_f32 v12, v80, v81
	v_cvt_pk_bf16_f32 v13, v82, v83
	v_cvt_pk_bf16_f32 v14, v84, v85
	v_cvt_pk_bf16_f32 v15, v86, v87
	global_store_dwordx4 v[20:21], v[12:15], off offset:-32
	v_lshlrev_b32_e32 v44, 16, v8
	v_and_b32_e32 v45, 0xffff0000, v8
	v_lshlrev_b32_e32 v8, 16, v9
	v_and_b32_e32 v9, 0xffff0000, v9
	v_lshlrev_b32_e32 v46, 16, v10
	v_and_b32_e32 v47, 0xffff0000, v10
	v_lshlrev_b32_e32 v10, 16, v11
	v_and_b32_e32 v11, 0xffff0000, v11
	v_pk_add_f32 v[88:89], v[88:89], v[44:45]
	v_pk_add_f32 v[90:91], v[90:91], v[8:9]
	v_pk_add_f32 v[92:93], v[92:93], v[46:47]
	v_pk_add_f32 v[94:95], v[94:95], v[10:11]
	v_cvt_pk_bf16_f32 v8, v88, v89
	v_cvt_pk_bf16_f32 v9, v90, v91
	v_cvt_pk_bf16_f32 v10, v92, v93
	v_cvt_pk_bf16_f32 v11, v94, v95
	global_store_dwordx4 v[20:21], v[8:11], off offset:-16
	v_lshlrev_b32_e32 v44, 16, v4
	v_and_b32_e32 v45, 0xffff0000, v4
	v_lshlrev_b32_e32 v4, 16, v5
	v_and_b32_e32 v5, 0xffff0000, v5
	v_lshlrev_b32_e32 v46, 16, v6
	v_and_b32_e32 v47, 0xffff0000, v6
	v_lshlrev_b32_e32 v6, 16, v7
	v_and_b32_e32 v7, 0xffff0000, v7
	v_pk_add_f32 v[96:97], v[96:97], v[44:45]
	v_pk_add_f32 v[98:99], v[98:99], v[4:5]
	v_pk_add_f32 v[100:101], v[100:101], v[46:47]
	v_pk_add_f32 v[102:103], v[102:103], v[6:7]
	v_cvt_pk_bf16_f32 v4, v96, v97
	v_cvt_pk_bf16_f32 v5, v98, v99
	v_cvt_pk_bf16_f32 v6, v100, v101
	v_cvt_pk_bf16_f32 v7, v102, v103
	global_store_dwordx4 v[20:21], v[4:7], off
	v_lshlrev_b32_e32 v44, 16, v0
	v_and_b32_e32 v45, 0xffff0000, v0
	v_lshlrev_b32_e32 v0, 16, v1
	v_and_b32_e32 v1, 0xffff0000, v1
	v_lshlrev_b32_e32 v46, 16, v2
	v_and_b32_e32 v47, 0xffff0000, v2
	v_lshlrev_b32_e32 v2, 16, v3
	v_and_b32_e32 v3, 0xffff0000, v3
	v_pk_add_f32 v[104:105], v[104:105], v[44:45]
	v_pk_add_f32 v[106:107], v[106:107], v[0:1]
	v_pk_add_f32 v[108:109], v[108:109], v[46:47]
	v_pk_add_f32 v[110:111], v[110:111], v[2:3]
	v_cvt_pk_bf16_f32 v0, v104, v105
	v_cvt_pk_bf16_f32 v1, v106, v107
	v_cvt_pk_bf16_f32 v2, v108, v109
	v_cvt_pk_bf16_f32 v3, v110, v111

.LBB0_581:
	s_or_b64 exec, exec, s[12:13]
	v_readlane_b32 s2, v252, 4
	v_and_b32_e32 v0, 0x1c0, v26
	v_mov_b32_e32 v1, 0x80
	s_nop 1
	s_lshr_b32 s2, s2, 3
	v_cmp_eq_u32_e32 vcc, 0, v0
	v_mov_b32_e32 v0, s2
	v_mov_b32_e32 v65, 0
	v_cndmask_b32_e32 v64, v1, v0, vcc
	s_movk_i32 s2, 0x80
	v_cmp_gt_i32_e32 vcc, s2, v64
	s_and_saveexec_b64 s[16:17], vcc
	s_cbranch_execz .LBB0_584
	s_load_dwordx2 s[2:3], s[6:7], 0x58
	v_and_b32_e32 v2, 7, v64
	v_lshlrev_b32_e32 v0, 2, v2
	v_mov_b32_e32 v1, 0
	v_mbcnt_hi_u32_b32 v4, -1, v220
	s_waitcnt lgkmcnt(0)
	v_lshl_add_u64 v[66:67], s[2:3], 0, v[0:1]
	v_lshlrev_b32_e32 v0, 18, v2
	v_lshl_add_u64 v[2:3], s[0:1], 0, v[0:1]
	v_lshlrev_b32_e32 v0, 8, v19
	v_lshl_add_u64 v[0:1], v[2:3], 0, v[0:1]
	s_mov_b64 s[2:3], 0x3aa0000
	v_and_b32_e32 v5, 64, v4
	v_lshl_add_u64 v[68:69], v[0:1], 0, s[2:3]
	v_add_u32_e32 v0, -1, v4
	v_cmp_lt_i32_e32 vcc, v0, v5
	s_ashr_i32 s95, s94, 31
	s_lshl_b64 s[18:19], s[94:95], 14
	v_cndmask_b32_e32 v0, v0, v4, vcc
	v_lshlrev_b32_e32 v78, 2, v0
	v_add_u32_e32 v0, -2, v4
	v_cmp_lt_i32_e64 s[4:5], v0, v5
	v_cmp_eq_u32_e32 vcc, 0, v19
	v_readlane_b32 s87, v252, 5
	v_cndmask_b32_e64 v0, v0, v4, s[4:5]
	v_lshlrev_b32_e32 v79, 2, v0
	v_add_u32_e32 v0, -4, v4
	v_cmp_lt_i32_e64 s[6:7], v0, v5
	v_cmp_gt_u32_e64 s[4:5], 2, v19
	s_mov_b64 s[20:21], 0
	v_cndmask_b32_e64 v0, v0, v4, s[6:7]
	v_lshlrev_b32_e32 v80, 2, v0
	v_add_u32_e32 v0, -8, v4
	v_cmp_lt_i32_e64 s[8:9], v0, v5
	v_cmp_gt_u32_e64 s[6:7], 4, v19
	s_mov_b32 s23, 0x42ce8ed0
	v_cndmask_b32_e64 v0, v0, v4, s[8:9]
	v_lshlrev_b32_e32 v81, 2, v0
	v_add_u32_e32 v0, -16, v4
	v_cmp_lt_i32_e64 s[10:11], v0, v5
	v_cmp_gt_u32_e64 s[8:9], 8, v19
	s_mov_b32 s24, 0xc2b17218
	v_cndmask_b32_e64 v0, v0, v4, s[10:11]
	v_lshlrev_b32_e32 v82, 2, v0
	v_subrev_u32_e32 v0, 32, v4
	v_cmp_lt_i32_e64 s[12:13], v0, v5
	v_cmp_gt_u32_e64 s[10:11], 16, v19
	s_mov_b32 s25, 0x7f800000
	v_cndmask_b32_e64 v0, v0, v4, s[12:13]
	v_lshlrev_b32_e32 v83, 2, v0
	v_lshlrev_b64 v[0:1], 14, v[64:65]
	v_lshl_or_b32 v0, v19, 8, v0
	v_lshl_add_u64 v[0:1], s[0:1], 0, v[0:1]
	s_mov_b64 s[0:1], 0x30a00f0
	v_cmp_gt_u32_e64 s[12:13], 32, v19
	v_lshl_add_u64 v[70:71], v[0:1], 0, s[0:1]
	s_mov_b32 s0, 0xbfb8aa3b
	s_mov_b32 s1, 0xb2a5705f
	v_mov_b32_e32 v65, 0x7f800000
	s_mov_b32 s26, 0x3f2aaaab
	v_mov_b32_e32 v84, 0x3ecc95a3
	s_mov_b32 s27, 0x3f317218
	s_mov_b32 s28, 0x33800000
	s_mov_b32 s22, 0x3fb8aa3b
	s_movk_i32 s29, 0x7f
	v_mov_b32_e32 v72, 0x3f317218

.LBB0_754:
	s_or_b64 exec, exec, s[14:15]
	v_ashrrev_i32_e32 v1, 6, v2
	v_readlane_b32 s3, v252, 4
	s_waitcnt lgkmcnt(0)
	s_barrier
	v_add_u32_e32 v0, s3, v1
	v_cmp_gt_i32_e32 vcc, s2, v0
	s_and_saveexec_b64 s[4:5], vcc
	s_cbranch_execz .LBB0_757
	v_and_b32_e32 v2, 63, v2
	v_lshl_add_u32 v11, v1, 6, s56
	v_ashrrev_i32_e32 v1, 31, v0
	v_lshlrev_b32_e32 v6, 2, v2
	v_lshlrev_b64 v[4:5], 9, v[0:1]
	v_or_b32_e32 v4, v4, v6
	v_mov_b32_e32 v3, 0
	v_lshl_add_u64 v[4:5], s[0:1], 0, v[4:5]
	s_mov_b64 s[6:7], 0x3ea0000
	s_ashr_i32 s95, s94, 31
	v_add_u32_e32 v10, 0, v6
	s_lshl_b32 s3, s90, 9
	v_lshl_add_u64 v[4:5], v[4:5], 0, s[6:7]
	s_lshl_b64 s[6:7], s[94:95], 9
	v_readlane_b32 s87, v252, 5
	s_mov_b64 s[8:9], 0
	s_movk_i32 s10, 0x2000
	v_mov_b32_e32 v1, 0x3da0000
	v_mov_b32_e32 v12, 0x3ca0000
	v_lshlrev_b32_e32 v6, 1, v2
	v_mov_b32_e32 v7, v3
	s_movk_i32 s11, 0x3fff
	v_ashrrev_i32_e32 v38, 6, v0
	v_and_b32_e32 v38, 0xffffff80, v38
	v_ashrrev_i32_e32 v39, 31, v38
	v_lshl_add_u64 v[38:39], v[38:39], 1, v[4:5]
	global_load_dword v40, v[38:39], off
	s_waitcnt vmcnt(0)
	s_branch .Lcmp2_body
.LBB0_756:
	s_waitcnt vmcnt(1)
.Lcmp2_body:
	v_add_u32_e32 v38, s94, v0
	v_lshl_add_u64 v[42:43], v[4:5], 0, s[6:7]
	v_ashrrev_i32_e32 v38, 6, v38
	v_and_b32_e32 v38, 0xffffff80, v38
	v_ashrrev_i32_e32 v39, 31, v38
	v_lshl_add_u64 v[38:39], v[38:39], 1, v[42:43]
	v_mov_b32_e32 v2, v40
	global_load_dword v40, v[38:39], off
	v_and_b32_e32 v8, 0x3fffe000, v0
	v_lshl_add_u32 v13, v8, 2, v10
	ds_read2st64_b32 v[8:9], v13 offset1:1
	ds_read2st64_b32 v[14:15], v13 offset0:2 offset1:3
	ds_read2st64_b32 v[16:17], v13 offset0:4 offset1:5
	ds_read2st64_b32 v[18:19], v13 offset0:6 offset1:7
	ds_read2st64_b32 v[20:21], v13 offset0:8 offset1:9
	ds_read2st64_b32 v[22:23], v13 offset0:10 offset1:11
	ds_read2st64_b32 v[24:25], v13 offset0:12 offset1:13
	ds_read2st64_b32 v[26:27], v13 offset0:14 offset1:15
	ds_read2st64_b32 v[30:31], v13 offset0:32 offset1:33
	ds_read2st64_b32 v[32:33], v13 offset0:34 offset1:35
	ds_read2st64_b32 v[34:35], v13 offset0:36 offset1:37
	v_cmp_gt_u32_e32 vcc, s10, v0
	v_add_u32_e32 v0, s94, v0
	v_lshl_add_u64 v[4:5], v[4:5], 0, s[6:7]
	ds_read2st64_b32 v[28:29], v13 offset0:30 offset1:31
	ds_read2st64_b32 v[36:37], v13 offset0:126 offset1:127
	v_readlane_b32 s2, v2, 0
	s_lshl_b32 s12, s2, 16
	s_and_b32 s13, s2, 0xffff0000
	v_readlane_b32 s2, v2, 1
	s_lshl_b32 s14, s2, 16
	s_and_b32 s15, s2, 0xffff0000
	v_readlane_b32 s2, v2, 2
	s_waitcnt lgkmcnt(12)
	v_pk_fma_f32 v[8:9], v[8:9], s[12:13], 0 op_sel_hi:[1,1,0]
	s_lshl_b32 s16, s2, 16
	s_and_b32 s17, s2, 0xffff0000
	v_readlane_b32 s2, v2, 3
	s_waitcnt lgkmcnt(11)
	v_pk_fma_f32 v[8:9], v[14:15], s[14:15], v[8:9]
	s_lshl_b32 s18, s2, 16
	s_and_b32 s19, s2, 0xffff0000
	v_readlane_b32 s2, v2, 4
	s_waitcnt lgkmcnt(10)
	v_pk_fma_f32 v[8:9], v[16:17], s[16:17], v[8:9]
	s_lshl_b32 s20, s2, 16
	s_and_b32 s21, s2, 0xffff0000
	v_readlane_b32 s2, v2, 5
	s_waitcnt lgkmcnt(9)
	v_pk_fma_f32 v[8:9], v[18:19], s[18:19], v[8:9]
	ds_read2st64_b32 v[14:15], v13 offset0:16 offset1:17
	ds_read2st64_b32 v[16:17], v13 offset0:18 offset1:19
	ds_read2st64_b32 v[18:19], v13 offset0:20 offset1:21
	s_lshl_b32 s22, s2, 16
	s_and_b32 s23, s2, 0xffff0000
	v_readlane_b32 s2, v2, 6
	s_waitcnt lgkmcnt(11)
	v_pk_fma_f32 v[8:9], v[20:21], s[20:21], v[8:9]
	s_lshl_b32 s24, s2, 16
	s_and_b32 s25, s2, 0xffff0000
	v_readlane_b32 s2, v2, 7
	s_waitcnt lgkmcnt(10)
	v_pk_fma_f32 v[8:9], v[22:23], s[22:23], v[8:9]
	s_lshl_b32 s26, s2, 16
	s_and_b32 s27, s2, 0xffff0000
	s_waitcnt lgkmcnt(9)
	v_pk_fma_f32 v[8:9], v[24:25], s[24:25], v[8:9]
	v_readlane_b32 s2, v2, 8
	ds_read2st64_b32 v[20:21], v13 offset0:22 offset1:23
	s_waitcnt lgkmcnt(9)
	v_pk_fma_f32 v[8:9], v[26:27], s[26:27], v[8:9]
	s_lshl_b32 s12, s2, 16
	s_and_b32 s13, s2, 0xffff0000
	v_readlane_b32 s2, v2, 9
	ds_read2st64_b32 v[22:23], v13 offset0:24 offset1:25
	ds_read2st64_b32 v[24:25], v13 offset0:26 offset1:27
	ds_read2st64_b32 v[26:27], v13 offset0:28 offset1:29
	s_lshl_b32 s14, s2, 16
	s_and_b32 s15, s2, 0xffff0000
	v_readlane_b32 s2, v2, 10
	s_waitcnt lgkmcnt(6)
	v_pk_fma_f32 v[8:9], v[14:15], s[12:13], v[8:9]
	s_lshl_b32 s16, s2, 16
	s_and_b32 s17, s2, 0xffff0000
	v_readlane_b32 s2, v2, 11
	s_waitcnt lgkmcnt(5)
	v_pk_fma_f32 v[8:9], v[16:17], s[14:15], v[8:9]
	s_lshl_b32 s18, s2, 16
	s_and_b32 s19, s2, 0xffff0000
	v_readlane_b32 s2, v2, 12
	s_waitcnt lgkmcnt(4)
	v_pk_fma_f32 v[8:9], v[18:19], s[16:17], v[8:9]
	s_lshl_b32 s20, s2, 16
	s_and_b32 s21, s2, 0xffff0000
	v_readlane_b32 s2, v2, 13
	s_waitcnt lgkmcnt(3)
	v_pk_fma_f32 v[8:9], v[20:21], s[18:19], v[8:9]
	s_lshl_b32 s22, s2, 16
	s_and_b32 s23, s2, 0xffff0000
	v_readlane_b32 s2, v2, 14
	s_waitcnt lgkmcnt(2)
	v_pk_fma_f32 v[8:9], v[22:23], s[20:21], v[8:9]
	s_lshl_b32 s24, s2, 16
	s_and_b32 s25, s2, 0xffff0000
	v_readlane_b32 s2, v2, 15
	s_waitcnt lgkmcnt(1)
	v_pk_fma_f32 v[8:9], v[24:25], s[22:23], v[8:9]
	s_lshl_b32 s26, s2, 16
	s_and_b32 s27, s2, 0xffff0000
	v_readlane_b32 s2, v2, 16
	s_waitcnt lgkmcnt(0)
	v_pk_fma_f32 v[8:9], v[26:27], s[24:25], v[8:9]
	ds_read2st64_b32 v[14:15], v13 offset0:38 offset1:39
	s_lshl_b32 s28, s2, 16
	s_and_b32 s29, s2, 0xffff0000
	v_readlane_b32 s2, v2, 17
	v_pk_fma_f32 v[8:9], v[28:29], s[26:27], v[8:9]
	ds_read2st64_b32 v[16:17], v13 offset0:40 offset1:41
	ds_read2st64_b32 v[18:19], v13 offset0:42 offset1:43
	ds_read2st64_b32 v[20:21], v13 offset0:44 offset1:45
	ds_read2st64_b32 v[22:23], v13 offset0:46 offset1:47
	s_lshl_b32 s30, s2, 16
	s_and_b32 s31, s2, 0xffff0000
	v_readlane_b32 s2, v2, 18
	v_pk_fma_f32 v[8:9], v[30:31], s[28:29], v[8:9]
	s_lshl_b32 s34, s2, 16
	s_and_b32 s35, s2, 0xffff0000
	v_pk_fma_f32 v[8:9], v[32:33], s[30:31], v[8:9]
	v_readlane_b32 s2, v2, 19
	v_pk_fma_f32 v[8:9], v[34:35], s[34:35], v[8:9]
	s_lshl_b32 s12, s2, 16
	s_and_b32 s13, s2, 0xffff0000
	v_readlane_b32 s2, v2, 20
	s_lshl_b32 s14, s2, 16
	s_and_b32 s15, s2, 0xffff0000
	v_readlane_b32 s2, v2, 21
	ds_read2st64_b32 v[24:25], v13 offset0:48 offset1:49
	ds_read2st64_b32 v[26:27], v13 offset0:50 offset1:51
	ds_read2st64_b32 v[28:29], v13 offset0:52 offset1:53
	ds_read2st64_b32 v[30:31], v13 offset0:54 offset1:55
	s_waitcnt lgkmcnt(8)
	v_pk_fma_f32 v[8:9], v[14:15], s[12:13], v[8:9]
	s_lshl_b32 s16, s2, 16
	s_and_b32 s17, s2, 0xffff0000
	v_readlane_b32 s2, v2, 22
	s_waitcnt lgkmcnt(7)
	v_pk_fma_f32 v[8:9], v[16:17], s[14:15], v[8:9]
	s_lshl_b32 s18, s2, 16
	s_and_b32 s19, s2, 0xffff0000
	v_readlane_b32 s2, v2, 23
	s_waitcnt lgkmcnt(6)
	v_pk_fma_f32 v[8:9], v[18:19], s[16:17], v[8:9]
	s_lshl_b32 s20, s2, 16
	s_and_b32 s21, s2, 0xffff0000
	v_readlane_b32 s2, v2, 24
	s_waitcnt lgkmcnt(5)
	v_pk_fma_f32 v[8:9], v[20:21], s[18:19], v[8:9]
	s_lshl_b32 s22, s2, 16
	s_and_b32 s23, s2, 0xffff0000
	v_readlane_b32 s2, v2, 25
	ds_read2st64_b32 v[32:33], v13 offset0:56 offset1:57
	ds_read2st64_b32 v[34:35], v13 offset0:58 offset1:59
	ds_read2st64_b32 v[14:15], v13 offset0:60 offset1:61
	ds_read2st64_b32 v[16:17], v13 offset0:62 offset1:63
	s_waitcnt lgkmcnt(8)
	v_pk_fma_f32 v[8:9], v[22:23], s[20:21], v[8:9]
	s_lshl_b32 s24, s2, 16
	s_and_b32 s25, s2, 0xffff0000
	v_readlane_b32 s2, v2, 26
	s_waitcnt lgkmcnt(7)
	v_pk_fma_f32 v[8:9], v[24:25], s[22:23], v[8:9]
	s_lshl_b32 s26, s2, 16
	s_and_b32 s27, s2, 0xffff0000
	v_readlane_b32 s2, v2, 27
	s_waitcnt lgkmcnt(6)
	v_pk_fma_f32 v[8:9], v[26:27], s[24:25], v[8:9]
	s_lshl_b32 s28, s2, 16
	s_and_b32 s29, s2, 0xffff0000
	v_readlane_b32 s2, v2, 28
	s_waitcnt lgkmcnt(5)
	v_pk_fma_f32 v[8:9], v[28:29], s[26:27], v[8:9]
	s_lshl_b32 s30, s2, 16
	s_and_b32 s31, s2, 0xffff0000
	v_readlane_b32 s2, v2, 29
	s_waitcnt lgkmcnt(4)
	v_pk_fma_f32 v[8:9], v[30:31], s[28:29], v[8:9]
	ds_read2st64_b32 v[18:19], v13 offset0:64 offset1:65
	ds_read2st64_b32 v[20:21], v13 offset0:66 offset1:67
	ds_read2st64_b32 v[22:23], v13 offset0:68 offset1:69
	ds_read2st64_b32 v[24:25], v13 offset0:70 offset1:71
	s_lshl_b32 s34, s2, 16
	s_and_b32 s35, s2, 0xffff0000
	s_waitcnt lgkmcnt(7)
	v_pk_fma_f32 v[8:9], v[32:33], s[30:31], v[8:9]
	v_readlane_b32 s2, v2, 30
	s_waitcnt lgkmcnt(6)
	v_pk_fma_f32 v[8:9], v[34:35], s[34:35], v[8:9]
	s_lshl_b32 s12, s2, 16
	s_and_b32 s13, s2, 0xffff0000
	v_readlane_b32 s2, v2, 31
	s_lshl_b32 s14, s2, 16
	s_and_b32 s15, s2, 0xffff0000
	v_readlane_b32 s2, v2, 32
	s_waitcnt lgkmcnt(5)
	v_pk_fma_f32 v[8:9], v[14:15], s[12:13], v[8:9]
	s_lshl_b32 s16, s2, 16
	s_and_b32 s17, s2, 0xffff0000
	v_readlane_b32 s2, v2, 33
	ds_read2st64_b32 v[26:27], v13 offset0:72 offset1:73
	ds_read2st64_b32 v[28:29], v13 offset0:74 offset1:75
	ds_read2st64_b32 v[30:31], v13 offset0:76 offset1:77
	ds_read2st64_b32 v[32:33], v13 offset0:78 offset1:79
	s_waitcnt lgkmcnt(8)
	v_pk_fma_f32 v[8:9], v[16:17], s[14:15], v[8:9]
	s_lshl_b32 s18, s2, 16
	s_and_b32 s19, s2, 0xffff0000
	v_readlane_b32 s2, v2, 34
	s_waitcnt lgkmcnt(7)
	v_pk_fma_f32 v[8:9], v[18:19], s[16:17], v[8:9]
	s_lshl_b32 s20, s2, 16
	s_and_b32 s21, s2, 0xffff0000
	v_readlane_b32 s2, v2, 35
	s_waitcnt lgkmcnt(6)
	v_pk_fma_f32 v[8:9], v[20:21], s[18:19], v[8:9]
	s_lshl_b32 s22, s2, 16
	s_and_b32 s23, s2, 0xffff0000
	v_readlane_b32 s2, v2, 36
	s_waitcnt lgkmcnt(5)
	v_pk_fma_f32 v[8:9], v[22:23], s[20:21], v[8:9]
	s_lshl_b32 s24, s2, 16
	s_and_b32 s25, s2, 0xffff0000
	v_readlane_b32 s2, v2, 37
	ds_read2st64_b32 v[34:35], v13 offset0:80 offset1:81
	ds_read2st64_b32 v[14:15], v13 offset0:82 offset1:83
	ds_read2st64_b32 v[16:17], v13 offset0:84 offset1:85
	ds_read2st64_b32 v[18:19], v13 offset0:86 offset1:87
	s_waitcnt lgkmcnt(8)
	v_pk_fma_f32 v[8:9], v[24:25], s[22:23], v[8:9]
	s_lshl_b32 s26, s2, 16
	s_and_b32 s27, s2, 0xffff0000
	v_readlane_b32 s2, v2, 38
	s_waitcnt lgkmcnt(7)
	v_pk_fma_f32 v[8:9], v[26:27], s[24:25], v[8:9]
	s_lshl_b32 s28, s2, 16
	s_and_b32 s29, s2, 0xffff0000
	v_readlane_b32 s2, v2, 39
	s_waitcnt lgkmcnt(6)
	v_pk_fma_f32 v[8:9], v[28:29], s[26:27], v[8:9]
	s_lshl_b32 s30, s2, 16
	s_and_b32 s31, s2, 0xffff0000
	v_readlane_b32 s2, v2, 40
	s_waitcnt lgkmcnt(5)
	v_pk_fma_f32 v[8:9], v[30:31], s[28:29], v[8:9]
	s_lshl_b32 s34, s2, 16
	s_and_b32 s35, s2, 0xffff0000
	s_waitcnt lgkmcnt(4)
	v_pk_fma_f32 v[8:9], v[32:33], s[30:31], v[8:9]
	v_readlane_b32 s2, v2, 41
	ds_read2st64_b32 v[20:21], v13 offset0:88 offset1:89
	ds_read2st64_b32 v[22:23], v13 offset0:90 offset1:91
	ds_read2st64_b32 v[24:25], v13 offset0:92 offset1:93
	ds_read2st64_b32 v[26:27], v13 offset0:94 offset1:95
	s_waitcnt lgkmcnt(7)
	v_pk_fma_f32 v[8:9], v[34:35], s[34:35], v[8:9]
	s_lshl_b32 s12, s2, 16
	s_and_b32 s13, s2, 0xffff0000
	v_readlane_b32 s2, v2, 42
	s_lshl_b32 s14, s2, 16
	s_and_b32 s15, s2, 0xffff0000
	v_readlane_b32 s2, v2, 43
	s_waitcnt lgkmcnt(6)
	v_pk_fma_f32 v[8:9], v[14:15], s[12:13], v[8:9]
	s_lshl_b32 s16, s2, 16
	s_and_b32 s17, s2, 0xffff0000
	v_readlane_b32 s2, v2, 44
	s_waitcnt lgkmcnt(5)
	v_pk_fma_f32 v[8:9], v[16:17], s[14:15], v[8:9]
	s_lshl_b32 s18, s2, 16
	s_and_b32 s19, s2, 0xffff0000
	v_readlane_b32 s2, v2, 45
	ds_read2st64_b32 v[28:29], v13 offset0:96 offset1:97
	ds_read2st64_b32 v[30:31], v13 offset0:98 offset1:99
	ds_read2st64_b32 v[32:33], v13 offset0:100 offset1:101
	ds_read2st64_b32 v[34:35], v13 offset0:102 offset1:103
	s_waitcnt lgkmcnt(8)
	v_pk_fma_f32 v[8:9], v[18:19], s[16:17], v[8:9]
	s_lshl_b32 s20, s2, 16
	s_and_b32 s21, s2, 0xffff0000
	v_readlane_b32 s2, v2, 46
	s_waitcnt lgkmcnt(7)
	v_pk_fma_f32 v[8:9], v[20:21], s[18:19], v[8:9]
	s_lshl_b32 s22, s2, 16
	s_and_b32 s23, s2, 0xffff0000
	v_readlane_b32 s2, v2, 47
	s_waitcnt lgkmcnt(6)
	v_pk_fma_f32 v[8:9], v[22:23], s[20:21], v[8:9]
	s_lshl_b32 s24, s2, 16
	s_and_b32 s25, s2, 0xffff0000
	v_readlane_b32 s2, v2, 48
	s_waitcnt lgkmcnt(5)
	v_pk_fma_f32 v[8:9], v[24:25], s[22:23], v[8:9]
	s_lshl_b32 s26, s2, 16
	s_and_b32 s27, s2, 0xffff0000
	v_readlane_b32 s2, v2, 49
	s_waitcnt lgkmcnt(4)
	v_pk_fma_f32 v[8:9], v[26:27], s[24:25], v[8:9]
	ds_read2st64_b32 v[14:15], v13 offset0:104 offset1:105
	ds_read2st64_b32 v[16:17], v13 offset0:106 offset1:107
	ds_read2st64_b32 v[18:19], v13 offset0:108 offset1:109
	ds_read2st64_b32 v[20:21], v13 offset0:110 offset1:111
	s_lshl_b32 s28, s2, 16
	s_and_b32 s29, s2, 0xffff0000
	v_readlane_b32 s2, v2, 50
	s_waitcnt lgkmcnt(7)
	v_pk_fma_f32 v[8:9], v[28:29], s[26:27], v[8:9]
	s_lshl_b32 s30, s2, 16
	s_and_b32 s31, s2, 0xffff0000
	v_readlane_b32 s2, v2, 51
	s_waitcnt lgkmcnt(6)
	v_pk_fma_f32 v[8:9], v[30:31], s[28:29], v[8:9]
	s_lshl_b32 s34, s2, 16
	s_and_b32 s35, s2, 0xffff0000
	s_waitcnt lgkmcnt(5)
	v_pk_fma_f32 v[8:9], v[32:33], s[30:31], v[8:9]
	v_readlane_b32 s2, v2, 52
	s_waitcnt lgkmcnt(4)
	v_pk_fma_f32 v[8:9], v[34:35], s[34:35], v[8:9]
	s_lshl_b32 s12, s2, 16
	s_and_b32 s13, s2, 0xffff0000
	v_readlane_b32 s2, v2, 53
	ds_read2st64_b32 v[22:23], v13 offset0:112 offset1:113
	ds_read2st64_b32 v[24:25], v13 offset0:114 offset1:115
	ds_read2st64_b32 v[26:27], v13 offset0:116 offset1:117
	ds_read2st64_b32 v[28:29], v13 offset0:118 offset1:119
	s_lshl_b32 s14, s2, 16
	s_and_b32 s15, s2, 0xffff0000
	v_readlane_b32 s2, v2, 54
	s_waitcnt lgkmcnt(7)
	v_pk_fma_f32 v[8:9], v[14:15], s[12:13], v[8:9]
	s_lshl_b32 s16, s2, 16
	s_and_b32 s17, s2, 0xffff0000
	v_readlane_b32 s2, v2, 55
	s_waitcnt lgkmcnt(6)
	v_pk_fma_f32 v[8:9], v[16:17], s[14:15], v[8:9]
	s_lshl_b32 s18, s2, 16
	s_and_b32 s19, s2, 0xffff0000
	v_readlane_b32 s2, v2, 56
	s_waitcnt lgkmcnt(5)
	v_pk_fma_f32 v[8:9], v[18:19], s[16:17], v[8:9]
	s_lshl_b32 s20, s2, 16
	s_and_b32 s21, s2, 0xffff0000
	v_readlane_b32 s2, v2, 57
	ds_read2st64_b32 v[30:31], v13 offset0:120 offset1:121
	ds_read2st64_b32 v[32:33], v13 offset0:122 offset1:123
	ds_read2st64_b32 v[34:35], v13 offset0:124 offset1:125
	s_waitcnt lgkmcnt(7)
	v_pk_fma_f32 v[8:9], v[20:21], s[18:19], v[8:9]
	s_lshl_b32 s22, s2, 16
	s_and_b32 s23, s2, 0xffff0000
	v_readlane_b32 s2, v2, 58
	s_waitcnt lgkmcnt(6)
	v_pk_fma_f32 v[8:9], v[22:23], s[20:21], v[8:9]
	s_lshl_b32 s24, s2, 16
	s_and_b32 s25, s2, 0xffff0000
	v_readlane_b32 s2, v2, 59
	s_waitcnt lgkmcnt(5)
	v_pk_fma_f32 v[8:9], v[24:25], s[22:23], v[8:9]
	s_lshl_b32 s26, s2, 16
	s_and_b32 s27, s2, 0xffff0000
	v_readlane_b32 s2, v2, 60
	s_waitcnt lgkmcnt(4)
	v_pk_fma_f32 v[8:9], v[26:27], s[24:25], v[8:9]
	s_lshl_b32 s28, s2, 16
	s_and_b32 s29, s2, 0xffff0000
	v_readlane_b32 s2, v2, 61
	s_waitcnt lgkmcnt(3)
	v_pk_fma_f32 v[8:9], v[28:29], s[26:27], v[8:9]
	s_lshl_b32 s30, s2, 16
	s_and_b32 s31, s2, 0xffff0000
	v_readlane_b32 s2, v2, 62
	s_waitcnt lgkmcnt(2)
	v_pk_fma_f32 v[8:9], v[30:31], s[28:29], v[8:9]
	s_lshl_b32 s34, s2, 16
	s_and_b32 s35, s2, 0xffff0000
	v_readlane_b32 s2, v2, 63
	s_waitcnt lgkmcnt(1)
	v_pk_fma_f32 v[8:9], v[32:33], s[30:31], v[8:9]
	v_cndmask_b32_e32 v2, v1, v12, vcc
	s_lshl_b32 s36, s2, 16
	s_and_b32 s37, s2, 0xffff0000
	s_waitcnt lgkmcnt(0)
	v_pk_fma_f32 v[8:9], v[34:35], s[34:35], v[8:9]
	v_lshl_add_u64 v[14:15], s[0:1], 0, v[2:3]
	v_and_b32_e32 v2, 0x7ffc0, v11
	v_pk_fma_f32 v[8:9], v[36:37], s[36:37], v[8:9]
	v_lshlrev_b32_e32 v2, 1, v2
	v_lshl_add_u64 v[14:15], v[14:15], 0, v[2:3]
	v_add_f32_e32 v2, v8, v9
	v_cmp_lt_i32_e32 vcc, s11, v0
	v_lshl_add_u64 v[14:15], v[14:15], 0, v[6:7]
	v_cvt_pk_bf16_f32 v2, v2, s0
	v_add_u32_e32 v11, s3, v11
	s_or_b64 s[8:9], vcc, s[8:9]
	global_store_short v[14:15], v2, off
	s_andn2_b64 exec, exec, s[8:9]
	s_cbranch_execnz .LBB0_756
